# un-serialized loads: router-weight LDS copy, FNet fold item, out_proj residual epilogue (all residual loads issued before stores)
# speedup vs baseline: 1.0845x; 1.0372x over previous
.LBB0_50:
	v_lshl_add_u64 v[8:9], v[6:7], 0, s[2:3]
	global_load_dword v110, v[8:9], off
	global_load_dword v111, v[8:9], off offset:256
	global_load_dword v112, v[8:9], off offset:512
	global_load_dword v113, v[8:9], off offset:768
	global_load_dword v114, v[8:9], off offset:1024
	global_load_dword v115, v[8:9], off offset:1280
	global_load_dword v116, v[8:9], off offset:1536
	global_load_dword v117, v[8:9], off offset:1792
	s_add_u32 s2, s2, 0x800
	s_addc_u32 s3, s3, 0
	v_and_b32_e32 v18, 56, v0
	v_cvt_f32_ubyte0_e32 v18, v18
	v_mul_f32_e32 v18, 0x3c800000, v18
	v_sin_f32_e32 v19, v18
	v_cos_f32_e32 v18, v18
	s_nop 0
	v_cndmask_b32_e32 v118, v19, v18, vcc
	v_add_u32_e32 v18, v2, v0
	v_and_b32_e32 v18, 63, v18
	v_cvt_f32_ubyte0_e32 v18, v18
	v_mul_f32_e32 v18, 0x3c800000, v18
	v_sin_f32_e32 v19, v18
	v_cos_f32_e32 v18, v18
	s_nop 0
	v_cndmask_b32_e32 v119, v19, v18, vcc
	v_add_u32_e32 v18, v16, v0
	v_and_b32_e32 v18, 62, v18
	v_cvt_f32_ubyte0_e32 v18, v18
	v_mul_f32_e32 v18, 0x3c800000, v18
	v_sin_f32_e32 v19, v18
	v_cos_f32_e32 v18, v18
	s_nop 0
	v_cndmask_b32_e32 v120, v19, v18, vcc
	v_add_u32_e32 v18, v15, v0
	v_and_b32_e32 v18, 63, v18
	v_cvt_f32_ubyte0_e32 v18, v18
	v_mul_f32_e32 v18, 0x3c800000, v18
	v_sin_f32_e32 v19, v18
	v_cos_f32_e32 v18, v18
	s_nop 0
	v_cndmask_b32_e32 v121, v19, v18, vcc
	v_add_u32_e32 v18, v14, v0
	v_and_b32_e32 v18, 60, v18
	v_cvt_f32_ubyte0_e32 v18, v18
	v_mul_f32_e32 v18, 0x3c800000, v18
	v_sin_f32_e32 v19, v18
	v_cos_f32_e32 v18, v18
	s_nop 0
	v_cndmask_b32_e32 v122, v19, v18, vcc
	v_add_u32_e32 v18, v13, v0
	v_and_b32_e32 v18, 63, v18
	v_cvt_f32_ubyte0_e32 v18, v18
	v_mul_f32_e32 v18, 0x3c800000, v18
	v_sin_f32_e32 v19, v18
	v_cos_f32_e32 v18, v18
	s_nop 0
	v_cndmask_b32_e32 v123, v19, v18, vcc
	v_add_u32_e32 v18, v12, v0
	v_and_b32_e32 v18, 62, v18
	v_cvt_f32_ubyte0_e32 v18, v18
	v_mul_f32_e32 v18, 0x3c800000, v18
	v_sin_f32_e32 v19, v18
	v_cos_f32_e32 v18, v18
	s_nop 0
	v_cndmask_b32_e32 v124, v19, v18, vcc
	v_add_u32_e32 v18, v5, v0
	v_and_b32_e32 v18, 63, v18
	v_cvt_f32_ubyte0_e32 v18, v18
	v_mul_f32_e32 v18, 0x3c800000, v18
	v_sin_f32_e32 v19, v18
	v_cos_f32_e32 v18, v18
	s_nop 0
	v_cndmask_b32_e32 v125, v19, v18, vcc
	v_add_u32_e32 v0, v0, v3
	s_waitcnt vmcnt(0)
	v_fmac_f32_e32 v17, v110, v118
	v_fmac_f32_e32 v17, v111, v119
	v_fmac_f32_e32 v17, v112, v120
	v_fmac_f32_e32 v17, v113, v121
	v_fmac_f32_e32 v17, v114, v122
	v_fmac_f32_e32 v17, v115, v123
	v_fmac_f32_e32 v17, v116, v124
	v_fmac_f32_e32 v17, v117, v125
	s_cmpk_eq_i32 s2, 0x4000
	s_cbranch_scc0 .LBB0_50
	v_mul_f32_e32 v0, 0x3e000000, v17
	v_ashrrev_i32_e32 v5, 31, v4
	v_cvt_pk_bf16_f32 v0, v0, s0
	v_lshl_add_u64 v[4:5], v[4:5], 1, s[58:59]
	global_store_short v[4:5], v0, off

.LBB0_751:
	s_lshr_b32 s0, s4, 11
	s_add_i32 s2, s0, 1
	s_and_b64 s[0:1], s[8:9], exec
	s_cselect_b32 s0, 0, s2
	s_mul_hi_u32 s1, s0, 0x6000
	s_mulk_i32 s0, 0x6000
	v_readlane_b32 s76, v253, 26
	s_waitcnt vmcnt(11)
	v_lshlrev_b32_e32 v64, 6, v140
	v_readlane_b32 s77, v253, 27
	s_add_u32 s2, s76, s0
	s_waitcnt vmcnt(10)
	v_or3_b32 v68, v64, s16, v141
	s_addc_u32 s3, s77, s1
	v_ashrrev_i32_e32 v69, 31, v68
	v_lshl_add_u64 v[64:65], v[68:69], 2, s[2:3]
	v_lshlrev_b32_e32 v69, 8, v138
	v_and_b32_e32 v69, 0x3000, v69
	s_mov_b64 s[2:3], 0x2000
	v_lshl_or_b32 v69, v139, 16, v69
	v_lshl_add_u64 v[70:71], v[64:65], 0, s[2:3]
	v_add_co_u32_e32 v64, vcc, s14, v64
	v_add_u32_e32 v112, v68, v69
	s_nop 0
	v_addc_co_u32_e32 v65, vcc, 0, v65, vcc
	v_lshlrev_b64 v[68:69], 2, v[112:113]
	global_load_dword v67, v[64:65], off
	global_load_dword v66, v[70:71], off offset:64
	s_nop 0
	global_load_dword v65, v[70:71], off offset:128
	global_load_dword v64, v[70:71], off offset:192
	v_lshl_add_u64 v[70:71], s[6:7], 0, v[68:69]
	v_readlane_b32 s78, v253, 28
	v_readlane_b32 s79, v253, 29
	v_readlane_b32 s80, v253, 30
	v_readlane_b32 s81, v253, 31
	v_readlane_b32 s82, v253, 32
	v_readlane_b32 s83, v253, 33
	v_readlane_b32 s84, v253, 34
	v_readlane_b32 s85, v253, 35
	v_readlane_b32 s86, v253, 36
	v_readlane_b32 s87, v253, 37
	v_readlane_b32 s88, v253, 38
	v_readlane_b32 s89, v253, 39
	v_readlane_b32 s90, v253, 40
	v_readlane_b32 s91, v253, 41
	v_readlane_b32 s76, v253, 50
	v_readlane_b32 s88, v253, 62
	v_readlane_b32 s89, v253, 63
	v_readlane_b32 s90, v255, 0
	v_readlane_b32 s91, v255, 1
	s_mov_b64 s[20:21], s[88:89]
	s_lshl_b64 s[0:1], s[18:19], 2
	s_mov_b64 s[22:23], s[90:91]
	s_add_u32 s0, s22, s0
	s_addc_u32 s1, s23, s1
	v_lshl_add_u64 v[68:69], s[0:1], 0, v[68:69]
	v_readlane_b32 s77, v253, 51
	v_readlane_b32 s78, v253, 52
	v_readlane_b32 s79, v253, 53
	v_readlane_b32 s80, v253, 54
	v_readlane_b32 s81, v253, 55
	v_readlane_b32 s82, v253, 56
	v_readlane_b32 s83, v253, 57
	v_readlane_b32 s84, v253, 58
	v_readlane_b32 s85, v253, 59
	v_readlane_b32 s86, v253, 60
	v_readlane_b32 s87, v253, 61
	v_lshlrev_b32_e32 v72, 2, v112
	s_mov_b64 s[98:99], s[6:7]
	global_load_dword v184, v72, s[98:99]
	global_load_dword v185, v72, s[98:99] offset:64
	global_load_dword v186, v72, s[98:99] offset:128
	global_load_dword v187, v72, s[98:99] offset:192
	s_add_u32 s98, s98, 0x1000
	s_addc_u32 s99, s99, 0
	global_load_dword v188, v72, s[98:99]
	global_load_dword v189, v72, s[98:99] offset:64
	global_load_dword v190, v72, s[98:99] offset:128
	global_load_dword v191, v72, s[98:99] offset:192
	s_add_u32 s98, s98, 0x1000
	s_addc_u32 s99, s99, 0
	global_load_dword v192, v72, s[98:99]
	global_load_dword v193, v72, s[98:99] offset:64
	global_load_dword v194, v72, s[98:99] offset:128
	global_load_dword v195, v72, s[98:99] offset:192
	s_add_u32 s98, s98, 0x1000
	s_addc_u32 s99, s99, 0
	global_load_dword v196, v72, s[98:99]
	global_load_dword v197, v72, s[98:99] offset:64
	global_load_dword v198, v72, s[98:99] offset:128
	global_load_dword v199, v72, s[98:99] offset:192
	s_add_u32 s98, s98, 0xd000
	s_addc_u32 s99, s99, 0
	global_load_dword v200, v72, s[98:99]
	global_load_dword v201, v72, s[98:99] offset:64
	global_load_dword v202, v72, s[98:99] offset:128
	global_load_dword v203, v72, s[98:99] offset:192
	s_add_u32 s98, s98, 0x1000
	s_addc_u32 s99, s99, 0
	global_load_dword v204, v72, s[98:99]
	global_load_dword v205, v72, s[98:99] offset:64
	global_load_dword v206, v72, s[98:99] offset:128
	global_load_dword v207, v72, s[98:99] offset:192
	s_add_u32 s98, s98, 0x1000
	s_addc_u32 s99, s99, 0
	global_load_dword v208, v72, s[98:99]
	global_load_dword v209, v72, s[98:99] offset:64
	global_load_dword v210, v72, s[98:99] offset:128
	global_load_dword v211, v72, s[98:99] offset:192
	s_add_u32 s98, s98, 0x1000
	s_addc_u32 s99, s99, 0
	global_load_dword v212, v72, s[98:99]
	global_load_dword v213, v72, s[98:99] offset:64
	global_load_dword v214, v72, s[98:99] offset:128
	global_load_dword v215, v72, s[98:99] offset:192
	s_add_u32 s98, s98, 0xd000
	s_addc_u32 s99, s99, 0
	global_load_dword v216, v72, s[98:99]
	global_load_dword v217, v72, s[98:99] offset:64
	global_load_dword v218, v72, s[98:99] offset:128
	global_load_dword v219, v72, s[98:99] offset:192
	s_add_u32 s98, s98, 0x1000
	s_addc_u32 s99, s99, 0
	global_load_dword v220, v72, s[98:99]
	global_load_dword v221, v72, s[98:99] offset:64
	global_load_dword v222, v72, s[98:99] offset:128
	global_load_dword v223, v72, s[98:99] offset:192
	s_add_u32 s98, s98, 0x1000
	s_addc_u32 s99, s99, 0
	global_load_dword v224, v72, s[98:99]
	global_load_dword v225, v72, s[98:99] offset:64
	global_load_dword v226, v72, s[98:99] offset:128
	global_load_dword v227, v72, s[98:99] offset:192
	s_add_u32 s98, s98, 0x1000
	s_addc_u32 s99, s99, 0
	global_load_dword v228, v72, s[98:99]
	global_load_dword v229, v72, s[98:99] offset:64
	global_load_dword v230, v72, s[98:99] offset:128
	global_load_dword v231, v72, s[98:99] offset:192
	s_add_u32 s98, s98, 0xd000
	s_addc_u32 s99, s99, 0
	global_load_dword v232, v72, s[98:99]
	global_load_dword v233, v72, s[98:99] offset:64
	global_load_dword v234, v72, s[98:99] offset:128
	global_load_dword v235, v72, s[98:99] offset:192
	s_add_u32 s98, s98, 0x1000
	s_addc_u32 s99, s99, 0
	global_load_dword v236, v72, s[98:99]
	global_load_dword v237, v72, s[98:99] offset:64
	global_load_dword v238, v72, s[98:99] offset:128
	global_load_dword v239, v72, s[98:99] offset:192
	s_add_u32 s98, s98, 0x1000
	s_addc_u32 s99, s99, 0
	s_waitcnt vmcnt(40)
	global_load_dword v240, v72, s[98:99]
	global_load_dword v241, v72, s[98:99] offset:64
	global_load_dword v242, v72, s[98:99] offset:128
	global_load_dword v243, v72, s[98:99] offset:192
	s_add_u32 s98, s98, 0x1000
	s_addc_u32 s99, s99, 0
	global_load_dword v244, v72, s[98:99]
	global_load_dword v245, v72, s[98:99] offset:64
	global_load_dword v246, v72, s[98:99] offset:128
	global_load_dword v247, v72, s[98:99] offset:192
	s_waitcnt vmcnt(0)
	v_mul_f32_e32 v184, 0x3fb504f3, v184
	v_fmac_f32_e32 v184, v60, v67
	global_store_dword v72, v184, s[0:1]
	v_mul_f32_e32 v185, 0x3fb504f3, v185
	v_fmac_f32_e32 v185, v56, v66
	global_store_dword v72, v185, s[0:1] offset:64
	v_mul_f32_e32 v186, 0x3fb504f3, v186
	v_fmac_f32_e32 v186, v52, v65
	global_store_dword v72, v186, s[0:1] offset:128
	v_mul_f32_e32 v187, 0x3fb504f3, v187
	v_fmac_f32_e32 v187, v48, v64
	global_store_dword v72, v187, s[0:1] offset:192
	s_add_u32 s0, s0, 0x1000
	s_addc_u32 s1, s1, 0
	v_mul_f32_e32 v188, 0x3fb504f3, v188
	v_fmac_f32_e32 v188, v61, v67
	global_store_dword v72, v188, s[0:1]
	v_mul_f32_e32 v189, 0x3fb504f3, v189
	v_fmac_f32_e32 v189, v57, v66
	global_store_dword v72, v189, s[0:1] offset:64
	v_mul_f32_e32 v190, 0x3fb504f3, v190
	v_fmac_f32_e32 v190, v53, v65
	global_store_dword v72, v190, s[0:1] offset:128
	v_mul_f32_e32 v191, 0x3fb504f3, v191
	v_fmac_f32_e32 v191, v49, v64
	global_store_dword v72, v191, s[0:1] offset:192
	s_add_u32 s0, s0, 0x1000
	s_addc_u32 s1, s1, 0
	v_mul_f32_e32 v192, 0x3fb504f3, v192
	v_fmac_f32_e32 v192, v62, v67
	global_store_dword v72, v192, s[0:1]
	v_mul_f32_e32 v193, 0x3fb504f3, v193
	v_fmac_f32_e32 v193, v58, v66
	global_store_dword v72, v193, s[0:1] offset:64
	v_mul_f32_e32 v194, 0x3fb504f3, v194
	v_fmac_f32_e32 v194, v54, v65
	global_store_dword v72, v194, s[0:1] offset:128
	v_mul_f32_e32 v195, 0x3fb504f3, v195
	v_fmac_f32_e32 v195, v50, v64
	global_store_dword v72, v195, s[0:1] offset:192
	s_add_u32 s0, s0, 0x1000
	s_addc_u32 s1, s1, 0
	v_mul_f32_e32 v196, 0x3fb504f3, v196
	v_fmac_f32_e32 v196, v63, v67
	global_store_dword v72, v196, s[0:1]
	v_mul_f32_e32 v197, 0x3fb504f3, v197
	v_fmac_f32_e32 v197, v59, v66
	global_store_dword v72, v197, s[0:1] offset:64
	v_mul_f32_e32 v198, 0x3fb504f3, v198
	v_fmac_f32_e32 v198, v55, v65
	global_store_dword v72, v198, s[0:1] offset:128
	v_mul_f32_e32 v199, 0x3fb504f3, v199
	v_fmac_f32_e32 v199, v51, v64
	global_store_dword v72, v199, s[0:1] offset:192
	s_add_u32 s0, s0, 0xd000
	s_addc_u32 s1, s1, 0
	v_mul_f32_e32 v200, 0x3fb504f3, v200
	v_fmac_f32_e32 v200, v44, v67
	global_store_dword v72, v200, s[0:1]
	v_mul_f32_e32 v201, 0x3fb504f3, v201
	v_fmac_f32_e32 v201, v40, v66
	global_store_dword v72, v201, s[0:1] offset:64
	v_mul_f32_e32 v202, 0x3fb504f3, v202
	v_fmac_f32_e32 v202, v36, v65
	global_store_dword v72, v202, s[0:1] offset:128
	v_mul_f32_e32 v203, 0x3fb504f3, v203
	v_fmac_f32_e32 v203, v32, v64
	global_store_dword v72, v203, s[0:1] offset:192
	s_add_u32 s0, s0, 0x1000
	s_addc_u32 s1, s1, 0
	v_mul_f32_e32 v204, 0x3fb504f3, v204
	v_fmac_f32_e32 v204, v45, v67
	global_store_dword v72, v204, s[0:1]
	v_mul_f32_e32 v205, 0x3fb504f3, v205
	v_fmac_f32_e32 v205, v41, v66
	global_store_dword v72, v205, s[0:1] offset:64
	v_mul_f32_e32 v206, 0x3fb504f3, v206
	v_fmac_f32_e32 v206, v37, v65
	global_store_dword v72, v206, s[0:1] offset:128
	v_mul_f32_e32 v207, 0x3fb504f3, v207
	v_fmac_f32_e32 v207, v33, v64
	global_store_dword v72, v207, s[0:1] offset:192
	s_add_u32 s0, s0, 0x1000
	s_addc_u32 s1, s1, 0
	v_mul_f32_e32 v208, 0x3fb504f3, v208
	v_fmac_f32_e32 v208, v46, v67
	global_store_dword v72, v208, s[0:1]
	v_mul_f32_e32 v209, 0x3fb504f3, v209
	v_fmac_f32_e32 v209, v42, v66
	global_store_dword v72, v209, s[0:1] offset:64
	v_mul_f32_e32 v210, 0x3fb504f3, v210
	v_fmac_f32_e32 v210, v38, v65
	global_store_dword v72, v210, s[0:1] offset:128
	v_mul_f32_e32 v211, 0x3fb504f3, v211
	v_fmac_f32_e32 v211, v34, v64
	global_store_dword v72, v211, s[0:1] offset:192
	s_add_u32 s0, s0, 0x1000
	s_addc_u32 s1, s1, 0
	v_mul_f32_e32 v212, 0x3fb504f3, v212
	v_fmac_f32_e32 v212, v47, v67
	global_store_dword v72, v212, s[0:1]
	v_mul_f32_e32 v213, 0x3fb504f3, v213
	v_fmac_f32_e32 v213, v43, v66
	global_store_dword v72, v213, s[0:1] offset:64
	v_mul_f32_e32 v214, 0x3fb504f3, v214
	v_fmac_f32_e32 v214, v39, v65
	global_store_dword v72, v214, s[0:1] offset:128
	v_mul_f32_e32 v215, 0x3fb504f3, v215
	v_fmac_f32_e32 v215, v35, v64
	global_store_dword v72, v215, s[0:1] offset:192
	s_add_u32 s0, s0, 0xd000
	s_addc_u32 s1, s1, 0
	v_mul_f32_e32 v216, 0x3fb504f3, v216
	v_fmac_f32_e32 v216, v28, v67
	global_store_dword v72, v216, s[0:1]
	v_mul_f32_e32 v217, 0x3fb504f3, v217
	v_fmac_f32_e32 v217, v24, v66
	global_store_dword v72, v217, s[0:1] offset:64
	v_mul_f32_e32 v218, 0x3fb504f3, v218
	v_fmac_f32_e32 v218, v20, v65
	global_store_dword v72, v218, s[0:1] offset:128
	v_mul_f32_e32 v219, 0x3fb504f3, v219
	v_fmac_f32_e32 v219, v16, v64
	global_store_dword v72, v219, s[0:1] offset:192
	s_add_u32 s0, s0, 0x1000
	s_addc_u32 s1, s1, 0
	v_mul_f32_e32 v220, 0x3fb504f3, v220
	v_fmac_f32_e32 v220, v29, v67
	global_store_dword v72, v220, s[0:1]
	v_mul_f32_e32 v221, 0x3fb504f3, v221
	v_fmac_f32_e32 v221, v25, v66
	global_store_dword v72, v221, s[0:1] offset:64
	v_mul_f32_e32 v222, 0x3fb504f3, v222
	v_fmac_f32_e32 v222, v21, v65
	global_store_dword v72, v222, s[0:1] offset:128
	v_mul_f32_e32 v223, 0x3fb504f3, v223
	v_fmac_f32_e32 v223, v17, v64
	global_store_dword v72, v223, s[0:1] offset:192
	s_add_u32 s0, s0, 0x1000
	s_addc_u32 s1, s1, 0
	v_mul_f32_e32 v224, 0x3fb504f3, v224
	v_fmac_f32_e32 v224, v30, v67
	global_store_dword v72, v224, s[0:1]
	v_mul_f32_e32 v225, 0x3fb504f3, v225
	v_fmac_f32_e32 v225, v26, v66
	global_store_dword v72, v225, s[0:1] offset:64
	v_mul_f32_e32 v226, 0x3fb504f3, v226
	v_fmac_f32_e32 v226, v22, v65
	global_store_dword v72, v226, s[0:1] offset:128
	v_mul_f32_e32 v227, 0x3fb504f3, v227
	v_fmac_f32_e32 v227, v18, v64
	global_store_dword v72, v227, s[0:1] offset:192
	s_add_u32 s0, s0, 0x1000
	s_addc_u32 s1, s1, 0
	v_mul_f32_e32 v228, 0x3fb504f3, v228
	v_fmac_f32_e32 v228, v31, v67
	global_store_dword v72, v228, s[0:1]
	v_mul_f32_e32 v229, 0x3fb504f3, v229
	v_fmac_f32_e32 v229, v27, v66
	global_store_dword v72, v229, s[0:1] offset:64
	v_mul_f32_e32 v230, 0x3fb504f3, v230
	v_fmac_f32_e32 v230, v23, v65
	global_store_dword v72, v230, s[0:1] offset:128
	v_mul_f32_e32 v231, 0x3fb504f3, v231
	v_fmac_f32_e32 v231, v19, v64
	global_store_dword v72, v231, s[0:1] offset:192
	s_add_u32 s0, s0, 0xd000
	s_addc_u32 s1, s1, 0
	v_mul_f32_e32 v232, 0x3fb504f3, v232
	v_fmac_f32_e32 v232, v8, v67
	global_store_dword v72, v232, s[0:1]
	v_mul_f32_e32 v233, 0x3fb504f3, v233
	v_fmac_f32_e32 v233, v4, v66
	global_store_dword v72, v233, s[0:1] offset:64
	v_mul_f32_e32 v234, 0x3fb504f3, v234
	v_fmac_f32_e32 v234, v0, v65
	global_store_dword v72, v234, s[0:1] offset:128
	v_mul_f32_e32 v235, 0x3fb504f3, v235
	v_fmac_f32_e32 v235, v12, v64
	global_store_dword v72, v235, s[0:1] offset:192
	s_add_u32 s0, s0, 0x1000
	s_addc_u32 s1, s1, 0
	v_mul_f32_e32 v236, 0x3fb504f3, v236
	v_fmac_f32_e32 v236, v9, v67
	global_store_dword v72, v236, s[0:1]
	v_mul_f32_e32 v237, 0x3fb504f3, v237
	v_fmac_f32_e32 v237, v5, v66
	global_store_dword v72, v237, s[0:1] offset:64
	v_mul_f32_e32 v238, 0x3fb504f3, v238
	v_fmac_f32_e32 v238, v1, v65
	global_store_dword v72, v238, s[0:1] offset:128
	v_mul_f32_e32 v239, 0x3fb504f3, v239
	v_fmac_f32_e32 v239, v13, v64
	global_store_dword v72, v239, s[0:1] offset:192
	s_add_u32 s0, s0, 0x1000
	s_addc_u32 s1, s1, 0
	v_mul_f32_e32 v240, 0x3fb504f3, v240
	v_fmac_f32_e32 v240, v10, v67
	global_store_dword v72, v240, s[0:1]
	v_mul_f32_e32 v241, 0x3fb504f3, v241
	v_fmac_f32_e32 v241, v6, v66
	global_store_dword v72, v241, s[0:1] offset:64
	v_mul_f32_e32 v242, 0x3fb504f3, v242
	v_fmac_f32_e32 v242, v2, v65
	global_store_dword v72, v242, s[0:1] offset:128
	v_mul_f32_e32 v243, 0x3fb504f3, v243
	v_fmac_f32_e32 v243, v14, v64
	global_store_dword v72, v243, s[0:1] offset:192
	s_add_u32 s0, s0, 0x1000
	s_addc_u32 s1, s1, 0
	v_mul_f32_e32 v244, 0x3fb504f3, v244
	v_fmac_f32_e32 v244, v11, v67
	global_store_dword v72, v244, s[0:1]
	v_mul_f32_e32 v245, 0x3fb504f3, v245
	v_fmac_f32_e32 v245, v7, v66
	global_store_dword v72, v245, s[0:1] offset:64
	v_mul_f32_e32 v246, 0x3fb504f3, v246
	v_fmac_f32_e32 v246, v3, v65
	global_store_dword v72, v246, s[0:1] offset:128
	v_mul_f32_e32 v247, 0x3fb504f3, v247
	v_fmac_f32_e32 v247, v15, v64
	global_store_dword v72, v247, s[0:1] offset:192
	s_add_i32 s15, s15, s92
	s_cmpk_lt_i32 s15, 0x200
	s_cbranch_scc0 .LBB0_778

.LBB0_832:
	s_mov_b64 s[2:3], s[8:9]
	global_load_dwordx4 v[168:171], v4, s[2:3]
	s_add_u32 s2, s2, 0x1000
	s_addc_u32 s3, s3, 0
	global_load_dwordx4 v[172:175], v4, s[2:3]
	s_add_u32 s2, s2, 0x1000
	s_addc_u32 s3, s3, 0
	global_load_dwordx4 v[176:179], v4, s[2:3]
	s_add_u32 s2, s2, 0x1000
	s_addc_u32 s3, s3, 0
	global_load_dwordx4 v[180:183], v4, s[2:3]
	s_add_u32 s2, s2, 0x1000
	s_addc_u32 s3, s3, 0
	global_load_dwordx4 v[184:187], v4, s[2:3]
	s_add_u32 s2, s2, 0x1000
	s_addc_u32 s3, s3, 0
	global_load_dwordx4 v[188:191], v4, s[2:3]
	s_add_u32 s2, s2, 0x1000
	s_addc_u32 s3, s3, 0
	global_load_dwordx4 v[192:195], v4, s[2:3]
	s_add_u32 s2, s2, 0x1000
	s_addc_u32 s3, s3, 0
	global_load_dwordx4 v[196:199], v4, s[2:3]
	s_add_u32 s2, s2, 0x1000
	s_addc_u32 s3, s3, 0
	global_load_dwordx4 v[200:203], v4, s[2:3]
	s_add_u32 s2, s2, 0x1000
	s_addc_u32 s3, s3, 0
	global_load_dwordx4 v[204:207], v4, s[2:3]
	s_add_u32 s2, s2, 0x1000
	s_addc_u32 s3, s3, 0
	global_load_dwordx4 v[208:211], v4, s[2:3]
	s_add_u32 s2, s2, 0x1000
	s_addc_u32 s3, s3, 0
	global_load_dwordx4 v[212:215], v4, s[2:3]
	s_add_u32 s2, s2, 0x1000
	s_addc_u32 s3, s3, 0
	global_load_dwordx4 v[216:219], v4, s[2:3]
	s_add_u32 s2, s2, 0x1000
	s_addc_u32 s3, s3, 0
	global_load_dwordx4 v[220:223], v4, s[2:3]
	s_add_u32 s2, s2, 0x1000
	s_addc_u32 s3, s3, 0
	global_load_dwordx4 v[224:227], v4, s[2:3]
	s_add_u32 s2, s2, 0x1000
	s_addc_u32 s3, s3, 0
	global_load_dwordx4 v[228:231], v4, s[2:3]
	s_waitcnt vmcnt(15)
	ds_write_b128 v4, v[168:171]
	s_waitcnt vmcnt(14)
	ds_write_b128 v4, v[172:175] offset:4096
	s_waitcnt vmcnt(13)
	ds_write_b128 v4, v[176:179] offset:8192
	s_waitcnt vmcnt(12)
	ds_write_b128 v4, v[180:183] offset:12288
	s_waitcnt vmcnt(11)
	ds_write_b128 v4, v[184:187] offset:16384
	s_waitcnt vmcnt(10)
	ds_write_b128 v4, v[188:191] offset:20480
	s_waitcnt vmcnt(9)
	ds_write_b128 v4, v[192:195] offset:24576
	s_waitcnt vmcnt(8)
	ds_write_b128 v4, v[196:199] offset:28672
	s_waitcnt vmcnt(7)
	ds_write_b128 v4, v[200:203] offset:32768
	s_waitcnt vmcnt(6)
	ds_write_b128 v4, v[204:207] offset:36864
	s_waitcnt vmcnt(5)
	ds_write_b128 v4, v[208:211] offset:40960
	s_waitcnt vmcnt(4)
	ds_write_b128 v4, v[212:215] offset:45056
	s_waitcnt vmcnt(3)
	ds_write_b128 v4, v[216:219] offset:49152
	s_waitcnt vmcnt(2)
	ds_write_b128 v4, v[220:223] offset:53248
	s_waitcnt vmcnt(1)
	ds_write_b128 v4, v[224:227] offset:57344
	s_waitcnt vmcnt(0)
	ds_write_b128 v4, v[228:231] offset:61440

.LBB0_1804:
	s_add_i32 s2, s14, 0xfffff000
	s_lshr_b32 s2, s2, 11
	s_add_i32 s2, s2, 4
	s_cmp_gt_i32 s30, 31
	v_readlane_b32 s76, v253, 26
	s_cselect_b32 s2, s2, 3
	v_readlane_b32 s77, v253, 27
	s_mul_hi_u32 s3, s2, 0x6000
	s_mulk_i32 s2, 0x6000
	s_mov_b64 s[36:37], s[76:77]
	s_waitcnt vmcnt(11)
	v_lshlrev_b32_e32 v64, 6, v126
	v_readlane_b32 s78, v253, 28
	v_readlane_b32 s79, v253, 29
	v_readlane_b32 s80, v253, 30
	v_readlane_b32 s81, v253, 31
	v_readlane_b32 s82, v253, 32
	v_readlane_b32 s83, v253, 33
	v_readlane_b32 s84, v253, 34
	v_readlane_b32 s85, v253, 35
	v_readlane_b32 s86, v253, 36
	v_readlane_b32 s87, v253, 37
	v_readlane_b32 s88, v253, 38
	v_readlane_b32 s89, v253, 39
	v_readlane_b32 s90, v253, 40
	v_readlane_b32 s91, v253, 41
	s_add_u32 s10, s36, s2
	v_or3_b32 v64, v64, s8, v127
	s_addc_u32 s11, s37, s3
	v_readlane_b32 s76, v253, 6
	v_ashrrev_i32_e32 v65, 31, v64
	v_readlane_b32 s77, v253, 7
	v_lshl_add_u64 v[66:67], v[64:65], 2, s[10:11]
	v_lshlrev_b32_e32 v65, 8, v124
	v_readlane_b32 s78, v253, 8
	v_readlane_b32 s79, v253, 9
	v_readlane_b32 s80, v253, 10
	v_readlane_b32 s81, v253, 11
	v_readlane_b32 s82, v253, 12
	v_readlane_b32 s83, v253, 13
	s_mov_b64 s[56:57], s[76:77]
	v_and_b32_e32 v65, 0x3000, v65
	s_lshl_b64 s[12:13], s[12:13], 2
	s_mov_b64 s[62:63], s[82:83]
	v_lshl_or_b32 v65, v125, 16, v65
	s_add_u32 s2, s62, s12
	v_add_u32_e32 v112, v64, v65
	s_addc_u32 s3, s63, s13
	v_lshlrev_b64 v[64:65], 2, v[112:113]
	s_waitcnt vmcnt(10)
	v_add_co_u32_e32 v68, vcc, s21, v66
	v_lshl_add_u64 v[70:71], s[2:3], 0, v[64:65]
	s_nop 0
	v_addc_co_u32_e32 v69, vcc, 0, v67, vcc
	global_load_dword v73, v[68:69], off
	v_readlane_b32 s84, v253, 14
	v_readlane_b32 s85, v253, 15
	v_readlane_b32 s86, v253, 16
	v_readlane_b32 s87, v253, 17
	v_readlane_b32 s88, v253, 18
	v_readlane_b32 s89, v253, 19
	v_readlane_b32 s90, v253, 20
	v_readlane_b32 s91, v253, 21
	s_mov_b64 s[58:59], s[78:79]
	s_mov_b64 s[60:61], s[80:81]
	v_readlane_b32 s76, v253, 50
	v_readlane_b32 s88, v253, 62
	v_readlane_b32 s89, v253, 63
	v_readlane_b32 s90, v255, 0
	v_readlane_b32 s91, v255, 1
	s_mov_b64 s[48:49], s[88:89]
	s_mov_b64 s[50:51], s[90:91]
	v_lshl_add_u64 v[66:67], v[66:67], 0, s[6:7]
	s_add_u32 s8, s50, s12
	global_load_dword v74, v[66:67], off offset:64
	global_load_dword v75, v[66:67], off offset:128
	global_load_dword v76, v[66:67], off offset:192
	s_addc_u32 s9, s51, s13
	v_lshl_add_u64 v[64:65], s[8:9], 0, v[64:65]
	v_mov_b32_e32 v67, v113
	v_readlane_b32 s77, v253, 51
	v_readlane_b32 s78, v253, 52
	v_readlane_b32 s79, v253, 53
	v_readlane_b32 s80, v253, 54
	v_readlane_b32 s81, v253, 55
	v_readlane_b32 s82, v253, 56
	v_readlane_b32 s83, v253, 57
	v_readlane_b32 s84, v253, 58
	v_readlane_b32 s85, v253, 59
	v_readlane_b32 s86, v253, 60
	v_readlane_b32 s87, v253, 61
	v_lshlrev_b32_e32 v72, 2, v112
	s_mov_b64 s[98:99], s[2:3]
	global_load_dword v184, v72, s[98:99]
	global_load_dword v185, v72, s[98:99] offset:64
	global_load_dword v186, v72, s[98:99] offset:128
	global_load_dword v187, v72, s[98:99] offset:192
	s_add_u32 s98, s98, 0x1000
	s_addc_u32 s99, s99, 0
	global_load_dword v188, v72, s[98:99]
	global_load_dword v189, v72, s[98:99] offset:64
	global_load_dword v190, v72, s[98:99] offset:128
	global_load_dword v191, v72, s[98:99] offset:192
	s_add_u32 s98, s98, 0x1000
	s_addc_u32 s99, s99, 0
	global_load_dword v192, v72, s[98:99]
	global_load_dword v193, v72, s[98:99] offset:64
	global_load_dword v194, v72, s[98:99] offset:128
	global_load_dword v195, v72, s[98:99] offset:192
	s_add_u32 s98, s98, 0x1000
	s_addc_u32 s99, s99, 0
	global_load_dword v196, v72, s[98:99]
	global_load_dword v197, v72, s[98:99] offset:64
	global_load_dword v198, v72, s[98:99] offset:128
	global_load_dword v199, v72, s[98:99] offset:192
	s_add_u32 s98, s98, 0xd000
	s_addc_u32 s99, s99, 0
	global_load_dword v200, v72, s[98:99]
	global_load_dword v201, v72, s[98:99] offset:64
	global_load_dword v202, v72, s[98:99] offset:128
	global_load_dword v203, v72, s[98:99] offset:192
	s_add_u32 s98, s98, 0x1000
	s_addc_u32 s99, s99, 0
	global_load_dword v204, v72, s[98:99]
	global_load_dword v205, v72, s[98:99] offset:64
	global_load_dword v206, v72, s[98:99] offset:128
	global_load_dword v207, v72, s[98:99] offset:192
	s_add_u32 s98, s98, 0x1000
	s_addc_u32 s99, s99, 0
	global_load_dword v208, v72, s[98:99]
	global_load_dword v209, v72, s[98:99] offset:64
	global_load_dword v210, v72, s[98:99] offset:128
	global_load_dword v211, v72, s[98:99] offset:192
	s_add_u32 s98, s98, 0x1000
	s_addc_u32 s99, s99, 0
	global_load_dword v212, v72, s[98:99]
	global_load_dword v213, v72, s[98:99] offset:64
	global_load_dword v214, v72, s[98:99] offset:128
	global_load_dword v215, v72, s[98:99] offset:192
	s_add_u32 s98, s98, 0xd000
	s_addc_u32 s99, s99, 0
	global_load_dword v216, v72, s[98:99]
	global_load_dword v217, v72, s[98:99] offset:64
	global_load_dword v218, v72, s[98:99] offset:128
	global_load_dword v219, v72, s[98:99] offset:192
	s_add_u32 s98, s98, 0x1000
	s_addc_u32 s99, s99, 0
	global_load_dword v220, v72, s[98:99]
	global_load_dword v221, v72, s[98:99] offset:64
	global_load_dword v222, v72, s[98:99] offset:128
	global_load_dword v223, v72, s[98:99] offset:192
	s_add_u32 s98, s98, 0x1000
	s_addc_u32 s99, s99, 0
	global_load_dword v224, v72, s[98:99]
	global_load_dword v225, v72, s[98:99] offset:64
	global_load_dword v226, v72, s[98:99] offset:128
	global_load_dword v227, v72, s[98:99] offset:192
	s_add_u32 s98, s98, 0x1000
	s_addc_u32 s99, s99, 0
	global_load_dword v228, v72, s[98:99]
	global_load_dword v229, v72, s[98:99] offset:64
	global_load_dword v230, v72, s[98:99] offset:128
	global_load_dword v231, v72, s[98:99] offset:192
	s_add_u32 s98, s98, 0xd000
	s_addc_u32 s99, s99, 0
	global_load_dword v232, v72, s[98:99]
	global_load_dword v233, v72, s[98:99] offset:64
	global_load_dword v234, v72, s[98:99] offset:128
	global_load_dword v235, v72, s[98:99] offset:192
	s_add_u32 s98, s98, 0x1000
	s_addc_u32 s99, s99, 0
	global_load_dword v236, v72, s[98:99]
	global_load_dword v237, v72, s[98:99] offset:64
	global_load_dword v238, v72, s[98:99] offset:128
	global_load_dword v239, v72, s[98:99] offset:192
	s_add_u32 s98, s98, 0x1000
	s_addc_u32 s99, s99, 0
	s_waitcnt vmcnt(40)
	global_load_dword v240, v72, s[98:99]
	global_load_dword v241, v72, s[98:99] offset:64
	global_load_dword v242, v72, s[98:99] offset:128
	global_load_dword v243, v72, s[98:99] offset:192
	s_add_u32 s98, s98, 0x1000
	s_addc_u32 s99, s99, 0
	global_load_dword v244, v72, s[98:99]
	global_load_dword v245, v72, s[98:99] offset:64
	global_load_dword v246, v72, s[98:99] offset:128
	global_load_dword v247, v72, s[98:99] offset:192
	s_waitcnt vmcnt(0)
	v_mul_f32_e32 v184, 0x3fb504f3, v184
	v_fmac_f32_e32 v184, v60, v73
	global_store_dword v72, v184, s[8:9]
	v_mul_f32_e32 v185, 0x3fb504f3, v185
	v_fmac_f32_e32 v185, v56, v74
	global_store_dword v72, v185, s[8:9] offset:64
	v_mul_f32_e32 v186, 0x3fb504f3, v186
	v_fmac_f32_e32 v186, v52, v75
	global_store_dword v72, v186, s[8:9] offset:128
	v_mul_f32_e32 v187, 0x3fb504f3, v187
	v_fmac_f32_e32 v187, v48, v76
	global_store_dword v72, v187, s[8:9] offset:192
	s_add_u32 s8, s8, 0x1000
	s_addc_u32 s9, s9, 0
	v_mul_f32_e32 v188, 0x3fb504f3, v188
	v_fmac_f32_e32 v188, v61, v73
	global_store_dword v72, v188, s[8:9]
	v_mul_f32_e32 v189, 0x3fb504f3, v189
	v_fmac_f32_e32 v189, v57, v74
	global_store_dword v72, v189, s[8:9] offset:64
	v_mul_f32_e32 v190, 0x3fb504f3, v190
	v_fmac_f32_e32 v190, v53, v75
	global_store_dword v72, v190, s[8:9] offset:128
	v_mul_f32_e32 v191, 0x3fb504f3, v191
	v_fmac_f32_e32 v191, v49, v76
	global_store_dword v72, v191, s[8:9] offset:192
	s_add_u32 s8, s8, 0x1000
	s_addc_u32 s9, s9, 0
	v_mul_f32_e32 v192, 0x3fb504f3, v192
	v_fmac_f32_e32 v192, v62, v73
	global_store_dword v72, v192, s[8:9]
	v_mul_f32_e32 v193, 0x3fb504f3, v193
	v_fmac_f32_e32 v193, v58, v74
	global_store_dword v72, v193, s[8:9] offset:64
	v_mul_f32_e32 v194, 0x3fb504f3, v194
	v_fmac_f32_e32 v194, v54, v75
	global_store_dword v72, v194, s[8:9] offset:128
	v_mul_f32_e32 v195, 0x3fb504f3, v195
	v_fmac_f32_e32 v195, v50, v76
	global_store_dword v72, v195, s[8:9] offset:192
	s_add_u32 s8, s8, 0x1000
	s_addc_u32 s9, s9, 0
	v_mul_f32_e32 v196, 0x3fb504f3, v196
	v_fmac_f32_e32 v196, v63, v73
	global_store_dword v72, v196, s[8:9]
	v_mul_f32_e32 v197, 0x3fb504f3, v197
	v_fmac_f32_e32 v197, v59, v74
	global_store_dword v72, v197, s[8:9] offset:64
	v_mul_f32_e32 v198, 0x3fb504f3, v198
	v_fmac_f32_e32 v198, v55, v75
	global_store_dword v72, v198, s[8:9] offset:128
	v_mul_f32_e32 v199, 0x3fb504f3, v199
	v_fmac_f32_e32 v199, v51, v76
	global_store_dword v72, v199, s[8:9] offset:192
	s_add_u32 s8, s8, 0xd000
	s_addc_u32 s9, s9, 0
	v_mul_f32_e32 v200, 0x3fb504f3, v200
	v_fmac_f32_e32 v200, v44, v73
	global_store_dword v72, v200, s[8:9]
	v_mul_f32_e32 v201, 0x3fb504f3, v201
	v_fmac_f32_e32 v201, v40, v74
	global_store_dword v72, v201, s[8:9] offset:64
	v_mul_f32_e32 v202, 0x3fb504f3, v202
	v_fmac_f32_e32 v202, v36, v75
	global_store_dword v72, v202, s[8:9] offset:128
	v_mul_f32_e32 v203, 0x3fb504f3, v203
	v_fmac_f32_e32 v203, v32, v76
	global_store_dword v72, v203, s[8:9] offset:192
	s_add_u32 s8, s8, 0x1000
	s_addc_u32 s9, s9, 0
	v_mul_f32_e32 v204, 0x3fb504f3, v204
	v_fmac_f32_e32 v204, v45, v73
	global_store_dword v72, v204, s[8:9]
	v_mul_f32_e32 v205, 0x3fb504f3, v205
	v_fmac_f32_e32 v205, v41, v74
	global_store_dword v72, v205, s[8:9] offset:64
	v_mul_f32_e32 v206, 0x3fb504f3, v206
	v_fmac_f32_e32 v206, v37, v75
	global_store_dword v72, v206, s[8:9] offset:128
	v_mul_f32_e32 v207, 0x3fb504f3, v207
	v_fmac_f32_e32 v207, v33, v76
	global_store_dword v72, v207, s[8:9] offset:192
	s_add_u32 s8, s8, 0x1000
	s_addc_u32 s9, s9, 0
	v_mul_f32_e32 v208, 0x3fb504f3, v208
	v_fmac_f32_e32 v208, v46, v73
	global_store_dword v72, v208, s[8:9]
	v_mul_f32_e32 v209, 0x3fb504f3, v209
	v_fmac_f32_e32 v209, v42, v74
	global_store_dword v72, v209, s[8:9] offset:64
	v_mul_f32_e32 v210, 0x3fb504f3, v210
	v_fmac_f32_e32 v210, v38, v75
	global_store_dword v72, v210, s[8:9] offset:128
	v_mul_f32_e32 v211, 0x3fb504f3, v211
	v_fmac_f32_e32 v211, v34, v76
	global_store_dword v72, v211, s[8:9] offset:192
	s_add_u32 s8, s8, 0x1000
	s_addc_u32 s9, s9, 0
	v_mul_f32_e32 v212, 0x3fb504f3, v212
	v_fmac_f32_e32 v212, v47, v73
	global_store_dword v72, v212, s[8:9]
	v_mul_f32_e32 v213, 0x3fb504f3, v213
	v_fmac_f32_e32 v213, v43, v74
	global_store_dword v72, v213, s[8:9] offset:64
	v_mul_f32_e32 v214, 0x3fb504f3, v214
	v_fmac_f32_e32 v214, v39, v75
	global_store_dword v72, v214, s[8:9] offset:128
	v_mul_f32_e32 v215, 0x3fb504f3, v215
	v_fmac_f32_e32 v215, v35, v76
	global_store_dword v72, v215, s[8:9] offset:192
	s_add_u32 s8, s8, 0xd000
	s_addc_u32 s9, s9, 0
	v_mul_f32_e32 v216, 0x3fb504f3, v216
	v_fmac_f32_e32 v216, v28, v73
	global_store_dword v72, v216, s[8:9]
	v_mul_f32_e32 v217, 0x3fb504f3, v217
	v_fmac_f32_e32 v217, v24, v74
	global_store_dword v72, v217, s[8:9] offset:64
	v_mul_f32_e32 v218, 0x3fb504f3, v218
	v_fmac_f32_e32 v218, v20, v75
	global_store_dword v72, v218, s[8:9] offset:128
	v_mul_f32_e32 v219, 0x3fb504f3, v219
	v_fmac_f32_e32 v219, v16, v76
	global_store_dword v72, v219, s[8:9] offset:192
	s_add_u32 s8, s8, 0x1000
	s_addc_u32 s9, s9, 0
	v_mul_f32_e32 v220, 0x3fb504f3, v220
	v_fmac_f32_e32 v220, v29, v73
	global_store_dword v72, v220, s[8:9]
	v_mul_f32_e32 v221, 0x3fb504f3, v221
	v_fmac_f32_e32 v221, v25, v74
	global_store_dword v72, v221, s[8:9] offset:64
	v_mul_f32_e32 v222, 0x3fb504f3, v222
	v_fmac_f32_e32 v222, v21, v75
	global_store_dword v72, v222, s[8:9] offset:128
	v_mul_f32_e32 v223, 0x3fb504f3, v223
	v_fmac_f32_e32 v223, v17, v76
	global_store_dword v72, v223, s[8:9] offset:192
	s_add_u32 s8, s8, 0x1000
	s_addc_u32 s9, s9, 0
	v_mul_f32_e32 v224, 0x3fb504f3, v224
	v_fmac_f32_e32 v224, v30, v73
	global_store_dword v72, v224, s[8:9]
	v_mul_f32_e32 v225, 0x3fb504f3, v225
	v_fmac_f32_e32 v225, v26, v74
	global_store_dword v72, v225, s[8:9] offset:64
	v_mul_f32_e32 v226, 0x3fb504f3, v226
	v_fmac_f32_e32 v226, v22, v75
	global_store_dword v72, v226, s[8:9] offset:128
	v_mul_f32_e32 v227, 0x3fb504f3, v227
	v_fmac_f32_e32 v227, v18, v76
	global_store_dword v72, v227, s[8:9] offset:192
	s_add_u32 s8, s8, 0x1000
	s_addc_u32 s9, s9, 0
	v_mul_f32_e32 v228, 0x3fb504f3, v228
	v_fmac_f32_e32 v228, v31, v73
	global_store_dword v72, v228, s[8:9]
	v_mul_f32_e32 v229, 0x3fb504f3, v229
	v_fmac_f32_e32 v229, v27, v74
	global_store_dword v72, v229, s[8:9] offset:64
	v_mul_f32_e32 v230, 0x3fb504f3, v230
	v_fmac_f32_e32 v230, v23, v75
	global_store_dword v72, v230, s[8:9] offset:128
	v_mul_f32_e32 v231, 0x3fb504f3, v231
	v_fmac_f32_e32 v231, v19, v76
	global_store_dword v72, v231, s[8:9] offset:192
	s_add_u32 s8, s8, 0xd000
	s_addc_u32 s9, s9, 0
	v_mul_f32_e32 v232, 0x3fb504f3, v232
	v_fmac_f32_e32 v232, v8, v73
	global_store_dword v72, v232, s[8:9]
	v_mul_f32_e32 v233, 0x3fb504f3, v233
	v_fmac_f32_e32 v233, v4, v74
	global_store_dword v72, v233, s[8:9] offset:64
	v_mul_f32_e32 v234, 0x3fb504f3, v234
	v_fmac_f32_e32 v234, v0, v75
	global_store_dword v72, v234, s[8:9] offset:128
	v_mul_f32_e32 v235, 0x3fb504f3, v235
	v_fmac_f32_e32 v235, v12, v76
	global_store_dword v72, v235, s[8:9] offset:192
	s_add_u32 s8, s8, 0x1000
	s_addc_u32 s9, s9, 0
	v_mul_f32_e32 v236, 0x3fb504f3, v236
	v_fmac_f32_e32 v236, v9, v73
	global_store_dword v72, v236, s[8:9]
	v_mul_f32_e32 v237, 0x3fb504f3, v237
	v_fmac_f32_e32 v237, v5, v74
	global_store_dword v72, v237, s[8:9] offset:64
	v_mul_f32_e32 v238, 0x3fb504f3, v238
	v_fmac_f32_e32 v238, v1, v75
	global_store_dword v72, v238, s[8:9] offset:128
	v_mul_f32_e32 v239, 0x3fb504f3, v239
	v_fmac_f32_e32 v239, v13, v76
	global_store_dword v72, v239, s[8:9] offset:192
	s_add_u32 s8, s8, 0x1000
	s_addc_u32 s9, s9, 0
	v_mul_f32_e32 v240, 0x3fb504f3, v240
	v_fmac_f32_e32 v240, v10, v73
	global_store_dword v72, v240, s[8:9]
	v_mul_f32_e32 v241, 0x3fb504f3, v241
	v_fmac_f32_e32 v241, v6, v74
	global_store_dword v72, v241, s[8:9] offset:64
	v_mul_f32_e32 v242, 0x3fb504f3, v242
	v_fmac_f32_e32 v242, v2, v75
	global_store_dword v72, v242, s[8:9] offset:128
	v_mul_f32_e32 v243, 0x3fb504f3, v243
	v_fmac_f32_e32 v243, v14, v76
	global_store_dword v72, v243, s[8:9] offset:192
	s_add_u32 s8, s8, 0x1000
	s_addc_u32 s9, s9, 0
	v_mul_f32_e32 v244, 0x3fb504f3, v244
	v_fmac_f32_e32 v244, v11, v73
	global_store_dword v72, v244, s[8:9]
	v_mul_f32_e32 v245, 0x3fb504f3, v245
	v_fmac_f32_e32 v245, v7, v74
	global_store_dword v72, v245, s[8:9] offset:64
	v_mul_f32_e32 v246, 0x3fb504f3, v246
	v_fmac_f32_e32 v246, v3, v75
	global_store_dword v72, v246, s[8:9] offset:128
	v_mul_f32_e32 v247, 0x3fb504f3, v247
	v_fmac_f32_e32 v247, v15, v76
	global_store_dword v72, v247, s[8:9] offset:192
	s_add_i32 s29, s29, s92
	s_cmpk_lt_i32 s29, 0x200
	s_cbranch_scc0 .LBB0_1811

.LBB0_1865:
	s_mov_b64 s[4:5], s[2:3]
	global_load_dwordx4 v[168:171], v4, s[4:5]
	s_add_u32 s4, s4, 0x1000
	s_addc_u32 s5, s5, 0
	global_load_dwordx4 v[172:175], v4, s[4:5]
	s_add_u32 s4, s4, 0x1000
	s_addc_u32 s5, s5, 0
	global_load_dwordx4 v[176:179], v4, s[4:5]
	s_add_u32 s4, s4, 0x1000
	s_addc_u32 s5, s5, 0
	global_load_dwordx4 v[180:183], v4, s[4:5]
	s_add_u32 s4, s4, 0x1000
	s_addc_u32 s5, s5, 0
	global_load_dwordx4 v[184:187], v4, s[4:5]
	s_add_u32 s4, s4, 0x1000
	s_addc_u32 s5, s5, 0
	global_load_dwordx4 v[188:191], v4, s[4:5]
	s_add_u32 s4, s4, 0x1000
	s_addc_u32 s5, s5, 0
	global_load_dwordx4 v[192:195], v4, s[4:5]
	s_add_u32 s4, s4, 0x1000
	s_addc_u32 s5, s5, 0
	global_load_dwordx4 v[196:199], v4, s[4:5]
	s_add_u32 s4, s4, 0x1000
	s_addc_u32 s5, s5, 0
	global_load_dwordx4 v[200:203], v4, s[4:5]
	s_add_u32 s4, s4, 0x1000
	s_addc_u32 s5, s5, 0
	global_load_dwordx4 v[204:207], v4, s[4:5]
	s_add_u32 s4, s4, 0x1000
	s_addc_u32 s5, s5, 0
	global_load_dwordx4 v[208:211], v4, s[4:5]
	s_add_u32 s4, s4, 0x1000
	s_addc_u32 s5, s5, 0
	global_load_dwordx4 v[212:215], v4, s[4:5]
	s_add_u32 s4, s4, 0x1000
	s_addc_u32 s5, s5, 0
	global_load_dwordx4 v[216:219], v4, s[4:5]
	s_add_u32 s4, s4, 0x1000
	s_addc_u32 s5, s5, 0
	global_load_dwordx4 v[220:223], v4, s[4:5]
	s_add_u32 s4, s4, 0x1000
	s_addc_u32 s5, s5, 0
	global_load_dwordx4 v[224:227], v4, s[4:5]
	s_add_u32 s4, s4, 0x1000
	s_addc_u32 s5, s5, 0
	global_load_dwordx4 v[228:231], v4, s[4:5]
	s_waitcnt vmcnt(15)
	ds_write_b128 v4, v[168:171]
	s_waitcnt vmcnt(14)
	ds_write_b128 v4, v[172:175] offset:4096
	s_waitcnt vmcnt(13)
	ds_write_b128 v4, v[176:179] offset:8192
	s_waitcnt vmcnt(12)
	ds_write_b128 v4, v[180:183] offset:12288
	s_waitcnt vmcnt(11)
	ds_write_b128 v4, v[184:187] offset:16384
	s_waitcnt vmcnt(10)
	ds_write_b128 v4, v[188:191] offset:20480
	s_waitcnt vmcnt(9)
	ds_write_b128 v4, v[192:195] offset:24576
	s_waitcnt vmcnt(8)
	ds_write_b128 v4, v[196:199] offset:28672
	s_waitcnt vmcnt(7)
	ds_write_b128 v4, v[200:203] offset:32768
	s_waitcnt vmcnt(6)
	ds_write_b128 v4, v[204:207] offset:36864
	s_waitcnt vmcnt(5)
	ds_write_b128 v4, v[208:211] offset:40960
	s_waitcnt vmcnt(4)
	ds_write_b128 v4, v[212:215] offset:45056
	s_waitcnt vmcnt(3)
	ds_write_b128 v4, v[216:219] offset:49152
	s_waitcnt vmcnt(2)
	ds_write_b128 v4, v[220:223] offset:53248
	s_waitcnt vmcnt(1)
	ds_write_b128 v4, v[224:227] offset:57344
	s_waitcnt vmcnt(0)
	ds_write_b128 v4, v[228:231] offset:61440
